# attention hot-tile address chains hoisted (MLA unmasked tiles, NSA selected-branch tile): fewer VALU per tile
# speedup vs baseline: 1.1449x; 1.0030x over previous
.LBB0_1890:
	s_or_b64 exec, exec, s[0:1]
	s_mov_b64 s[0:1], s[88:89]
	s_waitcnt lgkmcnt(0)
	v_mov_b32_e32 v0, v186
	s_mov_b32 s2, s90
	s_barrier
	s_nop 0
	v_readlane_b32 s2, v252, 34
	v_readlane_b32 s3, v252, 35
	s_andn2_b64 vcc, exec, s[2:3]
	s_cbranch_vccnz .LBB0_2024
	v_mov_b32_e32 v220, v186
	v_ashrrev_i32_e32 v221, 31, v220
	v_lshrrev_b32_e32 v222, 29, v221
	v_add_u32_e32 v223, v220, v222
	v_ashrrev_i32_e32 v224, 3, v223
	v_and_b32_e32 v225, 0xffffff8, v223
	v_lshlrev_b32_e32 v226, 2, v224
	v_lshrrev_b32_e32 v227, 1, v224
	v_sub_u32_e32 v228, v220, v225
	v_and_b32_e32 v229, 16, v226
	v_and_b32_e32 v230, 12, v227
	v_and_b32_e32 v231, 35, v224
	v_or3_b32 v232, v231, v229, v230
	v_lshlrev_b32_e32 v233, 4, v228
	v_mad_u32_u24 v234, v232, s43, v233
	v_mov_b32_e32 v214, v234
	v_mov_b32_e32 v220, v186
	v_lshlrev_b32_e32 v221, 4, v220
	v_and_b32_e32 v222, 0x70, v221
	v_lshrrev_b32_e32 v223, 3, v220
	v_mad_u64_u32 v[224:225], vcc, v223, s43, v[222:223]
	v_mov_b32_e32 v218, v224
	v_mov_b32_e32 v220, v186
	v_mul_hi_i32 v221, v220, s91
	v_lshrrev_b32_e32 v222, 31, v221
	v_ashrrev_i32_e32 v223, 1, v221
	v_add_u32_e32 v224, v223, v222
	v_mul_lo_u32 v225, v224, 12
	v_lshlrev_b32_e32 v226, 2, v224
	v_lshrrev_b32_e32 v227, 1, v224
	v_sub_u32_e32 v228, v220, v225
	v_and_b32_e32 v229, 16, v226
	v_and_b32_e32 v230, 12, v227
	v_and_b32_e32 v231, 35, v224
	v_or3_b32 v232, v231, v229, v230
	v_lshlrev_b32_e32 v233, 4, v228
	v_mad_u32_u24 v234, v232, s36, v233
	v_mov_b32_e32 v215, v234
	v_mov_b32_e32 v220, v186
	v_add_u32_e32 v221, 0x100, v220
	v_mul_hi_i32 v222, v221, s91
	v_lshrrev_b32_e32 v223, 31, v222
	v_ashrrev_i32_e32 v224, 1, v222
	v_add_u32_e32 v225, v224, v223
	v_mul_lo_u32 v226, v225, 12
	v_lshlrev_b32_e32 v227, 2, v225
	v_lshrrev_b32_e32 v228, 1, v225
	v_sub_u32_e32 v229, v221, v226
	v_and_b32_e32 v230, 16, v227
	v_and_b32_e32 v231, 12, v228
	v_and_b32_e32 v232, 35, v225
	v_or3_b32 v233, v232, v230, v231
	v_lshlrev_b32_e32 v234, 4, v229
	v_mad_u32_u24 v235, v233, s36, v234
	v_mov_b32_e32 v216, v235
	v_mov_b32_e32 v220, v186
	v_add_u32_e32 v221, 0x200, v220
	v_mul_hi_i32 v222, v221, s91
	v_lshrrev_b32_e32 v223, 31, v222
	v_ashrrev_i32_e32 v224, 1, v222
	v_add_u32_e32 v225, v224, v223
	v_mul_lo_u32 v226, v225, 12
	v_sub_u32_e32 v227, v221, v226
	v_lshlrev_b32_e32 v228, 2, v225
	v_lshrrev_b32_e32 v229, 1, v225
	v_and_b32_e32 v230, 16, v228
	v_and_b32_e32 v231, 12, v229
	v_and_b32_e32 v232, 35, v225
	v_or3_b32 v233, v232, v230, v231
	v_lshlrev_b32_e32 v234, 4, v227
	v_mad_u32_u24 v235, v233, s36, v234
	v_mov_b32_e32 v217, v235
	v_and_b32_e32 v246, 15, v186
	v_and_b32_e32 v247, 48, v186
	v_mad_u32_u24 v245, v246, s43, v247
	v_mad_u32_u24 v244, v246, s36, v247
	v_bfe_u32 v248, v186, 4, 2
	v_lshlrev_b32_e32 v248, 3, v248
	v_lshlrev_b32_e32 v219, 4, v186
	v_add_u32_e32 v236, 0x1000, v219
	v_add_u32_e32 v241, 0x2000, v219
	v_and_b32_e32 v220, 0x70, v219
	v_lshrrev_b32_e32 v221, 3, v186
	v_lshl_or_b32 v237, v221, 14, v220
	v_add_u32_e32 v238, 0x80000, v237
	v_lshl_or_b32 v239, v221, 10, v220
	v_add_u32_e32 v240, 0x8000, v239
	s_add_u32 s2, s0, 0x7000000
	s_addc_u32 s3, s1, 0
	v_writelane_b32 v254, s2, 36
	s_nop 1
	v_writelane_b32 v254, s3, 37
	s_add_u32 s2, s0, 0x8000000
	v_writelane_b32 v254, s2, 38
	s_addc_u32 s2, s1, 0
	v_writelane_b32 v254, s2, 39
	s_lshl_b32 s2, s22, 3
	s_mov_b32 s3, s77
	s_lshl_b64 s[2:3], s[2:3], 2
	s_add_u32 s2, s58, s2
	s_addc_u32 s3, s59, s3
	v_writelane_b32 v254, s2, 40
	s_nop 1
	v_writelane_b32 v254, s3, 41
	s_add_u32 s2, s0, 0x8400000
	v_writelane_b32 v254, s2, 42
	s_addc_u32 s2, s1, 0
	v_writelane_b32 v254, s2, 43
	s_add_u32 s2, s0, 0x4800000
	s_addc_u32 s3, s1, 0
	v_writelane_b32 v254, s2, 30
	s_nop 1
	v_writelane_b32 v254, s3, 31
	s_add_u32 s2, s0, 0x6400000
	v_writelane_b32 v254, s2, 44
	s_addc_u32 s2, s1, 0
	v_writelane_b32 v254, s2, 45
	s_add_u32 s2, s0, 0x6c00000
	v_writelane_b32 v254, s2, 46
	s_addc_u32 s2, s1, 0
	v_writelane_b32 v254, s2, 47
	s_add_u32 s2, s0, 0xe200000
	v_writelane_b32 v254, s2, 48
	s_addc_u32 s2, s1, 0
	v_writelane_b32 v254, s2, 49
	s_add_u32 s2, s0, 0x6000000
	v_writelane_b32 v254, s2, 50
	s_addc_u32 s2, s1, 0
	v_writelane_b32 v254, s2, 51
	s_add_u32 s2, s0, 0x6800000
	v_writelane_b32 v254, s2, 52
	s_addc_u32 s2, s1, 0
	v_writelane_b32 v254, s2, 53
	s_add_u32 s2, s0, 0x9800000
	s_addc_u32 s3, s1, 0
	v_writelane_b32 v254, s2, 54
	s_nop 1
	v_writelane_b32 v254, s3, 55
	s_add_u32 s2, s0, 0xe240000
	v_writelane_b32 v254, s2, 56
	s_addc_u32 s2, s1, 0
	v_writelane_b32 v254, s2, 57
	s_add_u32 s2, s0, 0x9a00000
	s_addc_u32 s3, s1, 0
	v_writelane_b32 v254, s2, 58
	s_nop 1
	v_writelane_b32 v254, s3, 59
	s_add_u32 s2, s0, 0xca00000
	v_writelane_b32 v254, s2, 60
	s_addc_u32 s2, s1, 0
	v_writelane_b32 v254, s2, 61
	s_add_u32 s2, s0, 0xb200000
	v_writelane_b32 v254, s2, 62
	s_addc_u32 s2, s1, 0
	v_writelane_b32 v254, s2, 63
	s_add_u32 s2, s0, 0x8800000
	v_writelane_b32 v255, s2, 0
	s_addc_u32 s2, s1, 0
	v_writelane_b32 v255, s2, 1
	s_add_u32 s2, s0, 0x8002000
	s_addc_u32 s3, s1, 0
	v_writelane_b32 v255, s2, 2
	v_readlane_b32 s41, v254, 16
	v_readlane_b32 s96, v254, 17
	v_writelane_b32 v255, s3, 3
	s_add_u32 s2, s0, 0xe202000
	v_writelane_b32 v255, s2, 4
	s_addc_u32 s2, s1, 0
	v_writelane_b32 v255, s2, 5
	s_add_u32 s2, s0, 0xe240080
	v_writelane_b32 v255, s2, 6
	s_addc_u32 s2, s1, 0
	v_writelane_b32 v255, s2, 7
	s_add_u32 s2, s0, 0x6802000
	v_writelane_b32 v255, s2, 8
	s_addc_u32 s2, s1, 0
	v_writelane_b32 v255, s2, 9
	s_add_u32 s0, s0, 0xb209000
	v_writelane_b32 v255, s0, 10
	s_addc_u32 s0, s1, 0
	v_writelane_b32 v255, s0, 11
	s_mov_b32 s80, s41
	s_mov_b32 s81, s41
	v_readlane_b32 s97, v254, 18
	v_readlane_b32 s40, v254, 14
	s_branch .LBB0_1894

.LBB0_1941:
	s_add_i32 s3, s2, 0xffffff40
	v_cmp_le_i32_e32 vcc, s3, v133
	s_and_saveexec_b64 s[8:9], vcc
	s_cbranch_execz .LBB0_1959
	s_add_i32 s3, s2, 0xffffff7f
	v_cmp_le_i32_e32 vcc, s3, v139
	s_and_saveexec_b64 s[10:11], vcc
	s_xor_b64 s[10:11], exec, s[10:11]
	s_cbranch_execz .LBB0_1950
	ds_read_b128 v[96:99], v244
	ds_read_b128 v[104:107], v244 offset:64
	ds_read_b128 v[108:111], v244 offset:3392
	ds_read_b128 v[116:119], v244 offset:6720
	ds_read_b128 v[124:127], v244 offset:6784
	ds_read_b128 v[142:145], v244 offset:10048
	s_waitcnt lgkmcnt(5)
	v_mfma_f32_16x16x32_bf16 v[100:103], v[96:99], v[16:19], 0
	v_mfma_f32_16x16x32_bf16 v[96:99], v[96:99], v[8:11], 0
	s_waitcnt lgkmcnt(4)
	v_mfma_f32_16x16x32_bf16 v[100:103], v[104:107], v[0:3], v[100:103]
	v_mfma_f32_16x16x32_bf16 v[96:99], v[104:107], v[12:15], v[96:99]
	ds_read_b128 v[104:107], v244 offset:128
	s_waitcnt lgkmcnt(0)
	v_mfma_f32_16x16x32_bf16 v[112:115], v[104:107], v[4:7], v[100:103]
	s_nop 3
	ds_read_b128 v[100:103], v244 offset:3328
	v_mfma_f32_16x16x32_bf16 v[96:99], v[104:107], v[20:23], v[96:99]
	s_waitcnt lgkmcnt(0)
	v_mfma_f32_16x16x32_bf16 v[104:107], v[100:103], v[16:19], 0
	v_mfma_f32_16x16x32_bf16 v[100:103], v[100:103], v[8:11], 0
	v_mfma_f32_16x16x32_bf16 v[104:107], v[108:111], v[0:3], v[104:107]
	v_mfma_f32_16x16x32_bf16 v[100:103], v[108:111], v[12:15], v[100:103]
	ds_read_b128 v[108:111], v244 offset:3456
	s_waitcnt lgkmcnt(0)
	v_mfma_f32_16x16x32_bf16 v[120:123], v[108:111], v[4:7], v[104:107]
	v_mfma_f32_16x16x32_bf16 v[104:107], v[108:111], v[20:23], v[100:103]
	s_nop 3
	ds_read_b128 v[100:103], v244 offset:6656
	s_waitcnt lgkmcnt(0)
	v_mfma_f32_16x16x32_bf16 v[108:111], v[100:103], v[16:19], 0
	v_mfma_f32_16x16x32_bf16 v[100:103], v[100:103], v[8:11], 0
	v_mfma_f32_16x16x32_bf16 v[108:111], v[116:119], v[0:3], v[108:111]
	v_mfma_f32_16x16x32_bf16 v[100:103], v[116:119], v[12:15], v[100:103]
	v_mfma_f32_16x16x32_bf16 v[116:119], v[124:127], v[4:7], v[108:111]
	s_nop 5
	ds_read_b128 v[108:111], v244 offset:9984
	v_mfma_f32_16x16x32_bf16 v[100:103], v[124:127], v[20:23], v[100:103]
	s_waitcnt lgkmcnt(0)
	v_mfma_f32_16x16x32_bf16 v[124:127], v[108:111], v[16:19], 0
	v_mfma_f32_16x16x32_bf16 v[108:111], v[108:111], v[8:11], 0
	v_mfma_f32_16x16x32_bf16 v[124:127], v[142:145], v[0:3], v[124:127]
	v_mfma_f32_16x16x32_bf16 v[108:111], v[142:145], v[12:15], v[108:111]
	ds_read_b128 v[142:145], v244 offset:10112
	s_waitcnt lgkmcnt(0)
	v_mfma_f32_16x16x32_bf16 v[124:127], v[142:145], v[4:7], v[124:127]
	v_mfma_f32_16x16x32_bf16 v[108:111], v[142:145], v[20:23], v[108:111]
	v_max_f32_e32 v142, v113, v112
	v_max3_f32 v142, v142, v114, v115
	v_max3_f32 v142, v142, v120, v121
	v_max3_f32 v142, v142, v122, v123
	v_max3_f32 v142, v142, v116, v117
	v_max3_f32 v142, v142, v118, v119
	s_nop 0
	v_max3_f32 v142, v142, v124, v125
	v_max3_f32 v142, v142, v126, v127
	v_sub_f32_e32 v143, v142, v136
	v_mul_f32_e32 v143, 0x3e16c740, v143
	v_cmp_lt_f32_e32 vcc, s42, v143
	s_cbranch_vccz .LBB0_1945
	v_mov_b32_e32 v143, v142
	s_nop 1
	v_permlane16_swap_b32_e32 v142, v143
	v_max_f32_e32 v142, v143, v142
	v_mov_b32_e32 v143, v142
	s_nop 1
	v_permlane32_swap_b32_e32 v142, v143
	v_max3_f32 v146, v136, v142, v143
	v_sub_f32_e32 v136, v136, v146
	v_mul_f32_e32 v136, 0x3e16c740, v136
	v_exp_f32_e32 v136, v136
	v_mov_b32_e32 v147, v137
	v_mul_f32_e32 v134, v134, v136
	v_pk_mul_f32 v[50:51], v[50:51], v[136:137] op_sel_hi:[1,0]
	v_pk_mul_f32 v[48:49], v[48:49], v[136:137] op_sel_hi:[1,0]
	v_pk_mul_f32 v[78:79], v[78:79], v[136:137] op_sel_hi:[1,0]
	v_pk_mul_f32 v[76:77], v[76:77], v[136:137] op_sel_hi:[1,0]
	v_pk_mul_f32 v[86:87], v[86:87], v[136:137] op_sel_hi:[1,0]
	v_pk_mul_f32 v[84:85], v[84:85], v[136:137] op_sel_hi:[1,0]
	v_pk_mul_f32 v[94:95], v[94:95], v[136:137] op_sel_hi:[1,0]
	v_pk_mul_f32 v[92:93], v[92:93], v[136:137] op_sel_hi:[1,0]
	v_mul_f32_e32 v136, 0xbe16c740, v146
	v_fmamk_f32 v112, v112, 0x3e16c740, v136
	v_exp_f32_e32 v142, v112
	v_fmamk_f32 v112, v113, 0x3e16c740, v136
	v_exp_f32_e32 v143, v112
	v_fmamk_f32 v112, v114, 0x3e16c740, v136
	v_exp_f32_e32 v144, v112
	v_fmamk_f32 v112, v115, 0x3e16c740, v136
	v_exp_f32_e32 v145, v112
	v_fmamk_f32 v113, v120, 0x3e16c740, v136
	v_add_f32_e32 v112, 0, v142
	v_exp_f32_e32 v120, v113
	v_fmamk_f32 v113, v121, 0x3e16c740, v136
	v_add_f32_e32 v112, v143, v112
	v_exp_f32_e32 v121, v113
	v_fmamk_f32 v113, v122, 0x3e16c740, v136
	v_add_f32_e32 v112, v144, v112
	v_exp_f32_e32 v122, v113
	v_fmamk_f32 v113, v123, 0x3e16c740, v136
	v_add_f32_e32 v112, v145, v112
	v_exp_f32_e32 v123, v113
	v_add_f32_e32 v112, v120, v112
	v_add_f32_e32 v112, v121, v112
	v_add_f32_e32 v112, v122, v112
	v_add_f32_e32 v137, v123, v112
	v_fmamk_f32 v112, v116, 0x3e16c740, v136
	v_exp_f32_e32 v112, v112
	v_fmamk_f32 v113, v117, 0x3e16c740, v136
	v_exp_f32_e32 v113, v113
	v_fmamk_f32 v114, v118, 0x3e16c740, v136
	v_exp_f32_e32 v114, v114
	v_fmamk_f32 v115, v119, 0x3e16c740, v136
	v_exp_f32_e32 v115, v115
	v_add_f32_e32 v116, v112, v137
	v_add_f32_e32 v116, v113, v116
	v_add_f32_e32 v116, v114, v116
	v_add_f32_e32 v137, v115, v116
	v_fmamk_f32 v116, v124, 0x3e16c740, v136
	v_exp_f32_e32 v116, v116
	v_fmamk_f32 v117, v125, 0x3e16c740, v136
	v_exp_f32_e32 v117, v117
	v_fmamk_f32 v118, v126, 0x3e16c740, v136
	v_exp_f32_e32 v118, v118
	v_fmac_f32_e32 v136, 0x3e16c740, v127
	v_exp_f32_e32 v119, v136
	v_add_f32_e32 v124, v116, v137
	v_add_f32_e32 v124, v117, v124
	v_add_f32_e32 v124, v118, v124
	v_add_f32_e32 v124, v119, v124
	v_mov_b64_e32 v[136:137], v[146:147]
	s_branch .LBB0_1946

.LBB0_1949:
	v_add_f32_e32 v96, v100, v96
	ds_read_b128 v[108:111], v245 offset:13312
	v_cvt_pk_bf16_f32 v140, v142, v143
	v_cvt_pk_bf16_f32 v141, v144, v145
	v_cvt_pk_bf16_f32 v142, v120, v121
	v_cvt_pk_bf16_f32 v143, v122, v123
	v_cvt_pk_bf16_f32 v120, v124, v125
	v_cvt_pk_bf16_f32 v121, v126, v127
	v_cvt_pk_bf16_f32 v122, v146, v105
	v_cvt_pk_bf16_f32 v123, v106, v107
	s_waitcnt lgkmcnt(0)
	v_mfma_f32_16x16x32_bf16 v[48:51], v[108:111], v[140:143], v[48:51]
	v_add_f32_e32 v96, v101, v96
	v_add_f32_e32 v96, v102, v96
	v_add_f32_e32 v96, v103, v96
	v_mfma_f32_16x16x32_bf16 v[40:43], v[108:111], v[120:123], v[40:43]
	ds_read_b128 v[106:109], v245 offset:15616
	v_add_f32_e32 v96, v104, v96
	v_cvt_pk_bf16_f32 v99, v99, v100
	v_cvt_pk_bf16_f32 v100, v101, v102
	v_cvt_pk_bf16_f32 v101, v103, v104
	ds_read_b128 v[102:105], v245 offset:15680
	s_waitcnt lgkmcnt(1)
	v_mfma_f32_16x16x32_bf16 v[76:79], v[106:109], v[140:143], v[76:79]
	v_cvt_pk_bf16_f32 v110, v112, v113
	v_cvt_pk_bf16_f32 v111, v114, v115
	v_cvt_pk_bf16_f32 v112, v116, v117
	v_mfma_f32_16x16x32_bf16 v[72:75], v[106:109], v[120:123], v[72:75]
	ds_read_b128 v[106:109], v245 offset:17920
	v_cvt_pk_bf16_f32 v113, v118, v119
	v_cvt_pk_bf16_f32 v98, v97, v98
	s_waitcnt lgkmcnt(0)
	v_mfma_f32_16x16x32_bf16 v[84:87], v[106:109], v[140:143], v[84:87]
	ds_read_b128 v[124:127], v245 offset:13376
	v_add_f32_e32 v135, v135, v96
	v_mfma_f32_16x16x32_bf16 v[76:79], v[102:105], v[110:113], v[76:79]
	v_mfma_f32_16x16x32_bf16 v[72:75], v[102:105], v[98:101], v[72:75]
	ds_read_b128 v[102:105], v245 offset:17984
	v_mfma_f32_16x16x32_bf16 v[80:83], v[106:109], v[120:123], v[80:83]
	ds_read_b128 v[106:109], v245 offset:20224
	s_waitcnt lgkmcnt(1)
	v_mfma_f32_16x16x32_bf16 v[84:87], v[102:105], v[110:113], v[84:87]
	v_mfma_f32_16x16x32_bf16 v[80:83], v[102:105], v[98:101], v[80:83]
	ds_read_b128 v[102:105], v245 offset:20288
	s_waitcnt lgkmcnt(1)
	v_mfma_f32_16x16x32_bf16 v[92:95], v[106:109], v[140:143], v[92:95]
	v_mfma_f32_16x16x32_bf16 v[88:91], v[106:109], v[120:123], v[88:91]
	v_mfma_f32_16x16x32_bf16 v[48:51], v[124:127], v[110:113], v[48:51]
	v_mfma_f32_16x16x32_bf16 v[40:43], v[124:127], v[98:101], v[40:43]
	s_waitcnt lgkmcnt(0)
	v_mfma_f32_16x16x32_bf16 v[92:95], v[102:105], v[110:113], v[92:95]
	v_mfma_f32_16x16x32_bf16 v[88:91], v[102:105], v[98:101], v[88:91]

.LBB0_1959:
	s_or_b64 exec, exec, s[8:9]
	s_add_i32 s3, s2, 0xffffff80
	v_cmp_le_i32_e32 vcc, s3, v133
	s_and_saveexec_b64 s[8:9], vcc
	s_cbranch_execz .LBB0_1938
	s_add_i32 s3, s2, 0xffffffbf
	v_cmp_le_i32_e32 vcc, s3, v139
	s_and_saveexec_b64 s[10:11], vcc
	s_xor_b64 s[10:11], exec, s[10:11]
	s_cbranch_execz .LBB0_1968
	ds_read_b128 v[96:99], v244 offset:22528
	ds_read_b128 v[104:107], v244 offset:22592
	ds_read_b128 v[108:111], v244 offset:25920
	ds_read_b128 v[116:119], v244 offset:29248
	ds_read_b128 v[124:127], v244 offset:29312
	ds_read_b128 v[142:145], v244 offset:32576
	s_waitcnt lgkmcnt(5)
	v_mfma_f32_16x16x32_bf16 v[100:103], v[96:99], v[16:19], 0
	v_mfma_f32_16x16x32_bf16 v[96:99], v[96:99], v[8:11], 0
	s_waitcnt lgkmcnt(4)
	v_mfma_f32_16x16x32_bf16 v[100:103], v[104:107], v[0:3], v[100:103]
	v_mfma_f32_16x16x32_bf16 v[96:99], v[104:107], v[12:15], v[96:99]
	ds_read_b128 v[104:107], v244 offset:22656
	s_waitcnt lgkmcnt(0)
	v_mfma_f32_16x16x32_bf16 v[112:115], v[104:107], v[4:7], v[100:103]
	s_nop 3
	ds_read_b128 v[100:103], v244 offset:25856
	v_mfma_f32_16x16x32_bf16 v[96:99], v[104:107], v[20:23], v[96:99]
	s_waitcnt lgkmcnt(0)
	v_mfma_f32_16x16x32_bf16 v[104:107], v[100:103], v[16:19], 0
	v_mfma_f32_16x16x32_bf16 v[100:103], v[100:103], v[8:11], 0
	v_mfma_f32_16x16x32_bf16 v[104:107], v[108:111], v[0:3], v[104:107]
	v_mfma_f32_16x16x32_bf16 v[100:103], v[108:111], v[12:15], v[100:103]
	ds_read_b128 v[108:111], v244 offset:25984
	s_waitcnt lgkmcnt(0)
	v_mfma_f32_16x16x32_bf16 v[120:123], v[108:111], v[4:7], v[104:107]
	v_mfma_f32_16x16x32_bf16 v[104:107], v[108:111], v[20:23], v[100:103]
	s_nop 3
	ds_read_b128 v[100:103], v244 offset:29184
	s_waitcnt lgkmcnt(0)
	v_mfma_f32_16x16x32_bf16 v[108:111], v[100:103], v[16:19], 0
	v_mfma_f32_16x16x32_bf16 v[100:103], v[100:103], v[8:11], 0
	v_mfma_f32_16x16x32_bf16 v[108:111], v[116:119], v[0:3], v[108:111]
	v_mfma_f32_16x16x32_bf16 v[100:103], v[116:119], v[12:15], v[100:103]
	v_mfma_f32_16x16x32_bf16 v[116:119], v[124:127], v[4:7], v[108:111]
	s_nop 5
	ds_read_b128 v[108:111], v244 offset:32512
	v_mfma_f32_16x16x32_bf16 v[100:103], v[124:127], v[20:23], v[100:103]
	s_waitcnt lgkmcnt(0)
	v_mfma_f32_16x16x32_bf16 v[124:127], v[108:111], v[16:19], 0
	v_mfma_f32_16x16x32_bf16 v[108:111], v[108:111], v[8:11], 0
	v_mfma_f32_16x16x32_bf16 v[124:127], v[142:145], v[0:3], v[124:127]
	v_mfma_f32_16x16x32_bf16 v[108:111], v[142:145], v[12:15], v[108:111]
	ds_read_b128 v[142:145], v244 offset:32640
	s_waitcnt lgkmcnt(0)
	v_mfma_f32_16x16x32_bf16 v[124:127], v[142:145], v[4:7], v[124:127]
	v_mfma_f32_16x16x32_bf16 v[108:111], v[142:145], v[20:23], v[108:111]
	v_max_f32_e32 v142, v113, v112
	v_max3_f32 v142, v142, v114, v115
	v_max3_f32 v142, v142, v120, v121
	v_max3_f32 v142, v142, v122, v123
	v_max3_f32 v142, v142, v116, v117
	v_max3_f32 v142, v142, v118, v119
	s_nop 0
	v_max3_f32 v142, v142, v124, v125
	v_max3_f32 v142, v142, v126, v127
	v_sub_f32_e32 v143, v142, v136
	v_mul_f32_e32 v143, 0x3e16c740, v143
	v_cmp_lt_f32_e32 vcc, s42, v143
	s_cbranch_vccz .LBB0_1963
	v_mov_b32_e32 v143, v142
	s_nop 1
	v_permlane16_swap_b32_e32 v142, v143
	v_max_f32_e32 v142, v143, v142
	v_mov_b32_e32 v143, v142
	s_nop 1
	v_permlane32_swap_b32_e32 v142, v143
	v_max3_f32 v146, v136, v142, v143
	v_sub_f32_e32 v136, v136, v146
	v_mul_f32_e32 v136, 0x3e16c740, v136
	v_exp_f32_e32 v136, v136
	v_mov_b32_e32 v147, v137
	v_mul_f32_e32 v134, v134, v136
	v_pk_mul_f32 v[50:51], v[50:51], v[136:137] op_sel_hi:[1,0]
	v_pk_mul_f32 v[48:49], v[48:49], v[136:137] op_sel_hi:[1,0]
	v_pk_mul_f32 v[78:79], v[78:79], v[136:137] op_sel_hi:[1,0]
	v_pk_mul_f32 v[76:77], v[76:77], v[136:137] op_sel_hi:[1,0]
	v_pk_mul_f32 v[86:87], v[86:87], v[136:137] op_sel_hi:[1,0]
	v_pk_mul_f32 v[84:85], v[84:85], v[136:137] op_sel_hi:[1,0]
	v_pk_mul_f32 v[94:95], v[94:95], v[136:137] op_sel_hi:[1,0]
	v_pk_mul_f32 v[92:93], v[92:93], v[136:137] op_sel_hi:[1,0]
	v_mul_f32_e32 v136, 0xbe16c740, v146
	v_fmamk_f32 v112, v112, 0x3e16c740, v136
	v_exp_f32_e32 v142, v112
	v_fmamk_f32 v112, v113, 0x3e16c740, v136
	v_exp_f32_e32 v143, v112
	v_fmamk_f32 v112, v114, 0x3e16c740, v136
	v_exp_f32_e32 v144, v112
	v_fmamk_f32 v112, v115, 0x3e16c740, v136
	v_exp_f32_e32 v145, v112
	v_fmamk_f32 v113, v120, 0x3e16c740, v136
	v_add_f32_e32 v112, 0, v142
	v_exp_f32_e32 v120, v113
	v_fmamk_f32 v113, v121, 0x3e16c740, v136
	v_add_f32_e32 v112, v143, v112
	v_exp_f32_e32 v121, v113
	v_fmamk_f32 v113, v122, 0x3e16c740, v136
	v_add_f32_e32 v112, v144, v112
	v_exp_f32_e32 v122, v113
	v_fmamk_f32 v113, v123, 0x3e16c740, v136
	v_add_f32_e32 v112, v145, v112
	v_exp_f32_e32 v123, v113
	v_add_f32_e32 v112, v120, v112
	v_add_f32_e32 v112, v121, v112
	v_add_f32_e32 v112, v122, v112
	v_add_f32_e32 v137, v123, v112
	v_fmamk_f32 v112, v116, 0x3e16c740, v136
	v_exp_f32_e32 v112, v112
	v_fmamk_f32 v113, v117, 0x3e16c740, v136
	v_exp_f32_e32 v113, v113
	v_fmamk_f32 v114, v118, 0x3e16c740, v136
	v_exp_f32_e32 v114, v114
	v_fmamk_f32 v115, v119, 0x3e16c740, v136
	v_exp_f32_e32 v115, v115
	v_add_f32_e32 v116, v112, v137
	v_add_f32_e32 v116, v113, v116
	v_add_f32_e32 v116, v114, v116
	v_add_f32_e32 v137, v115, v116
	v_fmamk_f32 v116, v124, 0x3e16c740, v136
	v_exp_f32_e32 v116, v116
	v_fmamk_f32 v117, v125, 0x3e16c740, v136
	v_exp_f32_e32 v117, v117
	v_fmamk_f32 v118, v126, 0x3e16c740, v136
	v_exp_f32_e32 v118, v118
	v_fmac_f32_e32 v136, 0x3e16c740, v127
	v_exp_f32_e32 v119, v136
	v_add_f32_e32 v124, v116, v137
	v_add_f32_e32 v124, v117, v124
	v_add_f32_e32 v124, v118, v124
	v_add_f32_e32 v124, v119, v124
	v_mov_b64_e32 v[136:137], v[146:147]
	s_branch .LBB0_1964

.LBB0_1967:
	v_add_f32_e32 v96, v100, v96
	ds_read_b128 v[108:111], v245 offset:35840
	v_cvt_pk_bf16_f32 v140, v142, v143
	v_cvt_pk_bf16_f32 v141, v144, v145
	v_cvt_pk_bf16_f32 v142, v120, v121
	v_cvt_pk_bf16_f32 v143, v122, v123
	v_cvt_pk_bf16_f32 v120, v124, v125
	v_cvt_pk_bf16_f32 v121, v126, v127
	v_cvt_pk_bf16_f32 v122, v146, v105
	v_cvt_pk_bf16_f32 v123, v106, v107
	s_waitcnt lgkmcnt(0)
	v_mfma_f32_16x16x32_bf16 v[48:51], v[108:111], v[140:143], v[48:51]
	v_add_f32_e32 v96, v101, v96
	v_add_f32_e32 v96, v102, v96
	v_add_f32_e32 v96, v103, v96
	v_mfma_f32_16x16x32_bf16 v[40:43], v[108:111], v[120:123], v[40:43]
	ds_read_b128 v[106:109], v245 offset:38144
	v_add_f32_e32 v96, v104, v96
	v_cvt_pk_bf16_f32 v99, v99, v100
	v_cvt_pk_bf16_f32 v100, v101, v102
	v_cvt_pk_bf16_f32 v101, v103, v104
	ds_read_b128 v[102:105], v245 offset:38208
	s_waitcnt lgkmcnt(1)
	v_mfma_f32_16x16x32_bf16 v[76:79], v[106:109], v[140:143], v[76:79]
	v_cvt_pk_bf16_f32 v110, v112, v113
	v_cvt_pk_bf16_f32 v111, v114, v115
	v_cvt_pk_bf16_f32 v112, v116, v117
	v_mfma_f32_16x16x32_bf16 v[72:75], v[106:109], v[120:123], v[72:75]
	ds_read_b128 v[106:109], v245 offset:40448
	v_cvt_pk_bf16_f32 v113, v118, v119
	v_cvt_pk_bf16_f32 v98, v97, v98
	s_waitcnt lgkmcnt(0)
	v_mfma_f32_16x16x32_bf16 v[84:87], v[106:109], v[140:143], v[84:87]
	ds_read_b128 v[124:127], v245 offset:35904
	v_add_f32_e32 v135, v135, v96
	v_mfma_f32_16x16x32_bf16 v[76:79], v[102:105], v[110:113], v[76:79]
	v_mfma_f32_16x16x32_bf16 v[72:75], v[102:105], v[98:101], v[72:75]
	ds_read_b128 v[102:105], v245 offset:40512
	v_mfma_f32_16x16x32_bf16 v[80:83], v[106:109], v[120:123], v[80:83]
	ds_read_b128 v[106:109], v245 offset:42752
	s_waitcnt lgkmcnt(1)
	v_mfma_f32_16x16x32_bf16 v[84:87], v[102:105], v[110:113], v[84:87]
	v_mfma_f32_16x16x32_bf16 v[80:83], v[102:105], v[98:101], v[80:83]
	ds_read_b128 v[102:105], v245 offset:42816
	s_waitcnt lgkmcnt(1)
	v_mfma_f32_16x16x32_bf16 v[92:95], v[106:109], v[140:143], v[92:95]
	v_mfma_f32_16x16x32_bf16 v[88:91], v[106:109], v[120:123], v[88:91]
	v_mfma_f32_16x16x32_bf16 v[48:51], v[124:127], v[110:113], v[48:51]
	v_mfma_f32_16x16x32_bf16 v[40:43], v[124:127], v[98:101], v[40:43]
	s_waitcnt lgkmcnt(0)
	v_mfma_f32_16x16x32_bf16 v[92:95], v[102:105], v[110:113], v[92:95]
	v_mfma_f32_16x16x32_bf16 v[88:91], v[102:105], v[98:101], v[88:91]

.LBB0_1997:
	s_lshr_b32 s0, s2, 5
	s_cmp_eq_u32 s0, 1
	s_cselect_b64 vcc, -1, 0
	s_cmp_eq_u32 s0, 2
	v_cndmask_b32_e32 v100, v80, v81, vcc
	s_cselect_b64 vcc, -1, 0
	s_cmp_eq_u32 s0, 3
	v_cndmask_b32_e32 v100, v100, v82, vcc
	s_cselect_b64 vcc, -1, 0
	v_cndmask_b32_e32 v100, v100, v83, vcc
	s_and_b32 s3, s2, 31
	v_bfe_u32 v100, v100, s3, 1
	v_cmp_ne_u32_e32 vcc, 0, v100
	s_nop 1
	s_mov_b64 s[0:1], vcc
	s_cbranch_vccz .LBB0_1992
	s_lshl_b32 s2, s2, 6
	ds_read_b128 v[100:103], v245
	ds_read_b128 v[104:107], v245 offset:64
	s_waitcnt lgkmcnt(1)
	v_mfma_f32_16x16x32_bf16 v[108:111], v[100:103], v[20:23], 0
	v_mfma_f32_16x16x32_bf16 v[100:103], v[100:103], v[28:31], 0
	s_waitcnt lgkmcnt(0)
	v_mfma_f32_16x16x32_bf16 v[108:111], v[104:107], v[24:27], v[108:111]
	v_mfma_f32_16x16x32_bf16 v[100:103], v[104:107], v[32:35], v[100:103]
	ds_read_b128 v[104:107], v245 offset:2304
	ds_read_b128 v[112:115], v245 offset:2368
	ds_read_b128 v[132:135], v245 offset:4608
	ds_read_b128 v[152:155], v245 offset:4672
	s_waitcnt lgkmcnt(3)
	v_mfma_f32_16x16x32_bf16 v[124:127], v[104:107], v[20:23], 0
	v_mfma_f32_16x16x32_bf16 v[104:107], v[104:107], v[28:31], 0
	s_waitcnt lgkmcnt(2)
	v_mfma_f32_16x16x32_bf16 v[138:141], v[112:115], v[24:27], v[124:127]
	s_nop 4
	v_subrev_u32_e32 v124, s2, v120
	v_mfma_f32_16x16x32_bf16 v[104:107], v[112:115], v[32:35], v[104:107]
	ds_read_b128 v[112:115], v245 offset:6912
	ds_read_b128 v[156:159], v245 offset:6976
	v_cndmask_b32_e64 v124, -1, v124, s[0:1]
	v_sub_u32_e32 v136, v124, v248
	s_waitcnt lgkmcnt(3)
	v_mfma_f32_16x16x32_bf16 v[164:167], v[132:135], v[20:23], 0
	v_cmp_gt_i32_e64 s[0:1], 0, v136
	v_cmp_gt_i32_e64 s[2:3], 1, v136
	v_cmp_gt_i32_e64 s[4:5], 2, v136
	v_mfma_f32_16x16x32_bf16 v[168:171], v[132:135], v[28:31], 0
	v_cmp_gt_i32_e64 s[6:7], 3, v136
	v_cndmask_b32_e64 v127, v108, v207, s[0:1]
	v_cndmask_b32_e64 v131, v109, v207, s[2:3]
	v_cndmask_b32_e64 v133, v110, v207, s[4:5]
	v_cndmask_b32_e64 v135, v111, v207, s[6:7]
	s_waitcnt lgkmcnt(2)
	v_mfma_f32_16x16x32_bf16 v[164:167], v[152:155], v[24:27], v[164:167]
	v_cmp_gt_i32_e64 s[8:9], 4, v136
	v_cmp_gt_i32_e64 s[10:11], 5, v136
	v_cmp_gt_i32_e64 s[14:15], 6, v136
	v_mfma_f32_16x16x32_bf16 v[108:111], v[152:155], v[32:35], v[168:171]
	v_cmp_gt_i32_e64 s[16:17], 7, v136
	v_cndmask_b32_e64 v137, v138, v207, s[8:9]
	v_cndmask_b32_e64 v138, v139, v207, s[10:11]
	s_waitcnt lgkmcnt(1)
	v_mfma_f32_16x16x32_bf16 v[152:155], v[112:115], v[20:23], 0
	v_cndmask_b32_e64 v139, v140, v207, s[14:15]
	v_cndmask_b32_e64 v140, v141, v207, s[16:17]
	v_max_f32_e32 v141, v131, v127
	s_waitcnt lgkmcnt(0)
	v_mfma_f32_16x16x32_bf16 v[152:155], v[156:159], v[24:27], v[152:155]
	v_max3_f32 v141, v141, v133, v135
	v_cmp_gt_i32_e64 s[18:19], 32, v136
	v_cmp_gt_i32_e64 s[20:21], 33, v136
	v_max3_f32 v141, v141, v137, v138
	v_cndmask_b32_e64 v123, v164, v207, s[18:19]
	v_cndmask_b32_e64 v124, v165, v207, s[20:21]
	v_mfma_f32_16x16x32_bf16 v[112:115], v[112:115], v[28:31], 0
	v_cmp_gt_i32_e64 s[22:23], 34, v136
	v_cmp_gt_i32_e64 s[24:25], 35, v136
	v_max3_f32 v141, v141, v139, v140
	v_cndmask_b32_e64 v125, v166, v207, s[22:23]
	v_cndmask_b32_e64 v126, v167, v207, s[24:25]
	v_cmp_gt_i32_e64 s[26:27], 36, v136
	v_cmp_gt_i32_e64 s[28:29], 37, v136
	v_max3_f32 v141, v141, v123, v124
	v_cndmask_b32_e64 v130, v152, v207, s[26:27]
	v_cndmask_b32_e64 v132, v153, v207, s[28:29]
	v_cmp_gt_i32_e64 s[30:31], 38, v136
	v_cmp_gt_i32_e64 s[34:35], 39, v136
	v_max3_f32 v141, v141, v125, v126
	v_cndmask_b32_e64 v134, v154, v207, s[30:31]
	v_cndmask_b32_e64 v136, v155, v207, s[34:35]
	v_max3_f32 v141, v141, v130, v132
	v_mfma_f32_16x16x32_bf16 v[112:115], v[156:159], v[32:35], v[112:115]
	v_max3_f32 v141, v141, v134, v136
	v_sub_f32_e32 v142, v141, v116
	v_mul_f32_e32 v142, 0x3e38aa3b, v142
	v_cmp_lt_f32_e32 vcc, s42, v142
	s_cbranch_vccz .LBB0_2003
	v_mov_b32_e32 v142, v141
	s_nop 1
	v_permlane16_swap_b32_e32 v141, v142
	v_max_f32_e32 v141, v142, v141
	v_mov_b32_e32 v142, v141
	s_nop 1
	v_permlane32_swap_b32_e32 v141, v142
	v_max3_f32 v142, v116, v141, v142
	v_sub_f32_e32 v116, v116, v142
	v_mul_f32_e32 v116, 0x3e38aa3b, v116
	v_exp_f32_e32 v116, v116
	v_mov_b32_e32 v143, v117
	v_mul_f32_e32 v118, v118, v116
	v_pk_mul_f32 v[50:51], v[50:51], v[116:117] op_sel_hi:[1,0]
	v_pk_mul_f32 v[48:49], v[48:49], v[116:117] op_sel_hi:[1,0]
	v_pk_mul_f32 v[54:55], v[54:55], v[116:117] op_sel_hi:[1,0]
	v_pk_mul_f32 v[52:53], v[52:53], v[116:117] op_sel_hi:[1,0]
	v_pk_mul_f32 v[58:59], v[58:59], v[116:117] op_sel_hi:[1,0]
	v_pk_mul_f32 v[56:57], v[56:57], v[116:117] op_sel_hi:[1,0]
	v_pk_mul_f32 v[62:63], v[62:63], v[116:117] op_sel_hi:[1,0]
	v_pk_mul_f32 v[60:61], v[60:61], v[116:117] op_sel_hi:[1,0]
	v_mul_f32_e32 v116, 0xbe38aa3b, v142
	v_fmamk_f32 v117, v127, 0x3e38aa3b, v116
	v_exp_f32_e32 v127, v117
	v_fmamk_f32 v117, v131, 0x3e38aa3b, v116
	v_exp_f32_e32 v131, v117
	v_fmamk_f32 v117, v133, 0x3e38aa3b, v116
	v_exp_f32_e32 v133, v117
	v_fmamk_f32 v117, v135, 0x3e38aa3b, v116
	v_exp_f32_e32 v135, v117
	v_fmamk_f32 v137, v137, 0x3e38aa3b, v116
	v_add_f32_e32 v117, 0, v127
	v_exp_f32_e32 v137, v137
	v_fmamk_f32 v138, v138, 0x3e38aa3b, v116
	v_add_f32_e32 v117, v131, v117
	v_exp_f32_e32 v138, v138
	v_fmamk_f32 v139, v139, 0x3e38aa3b, v116
	v_add_f32_e32 v117, v133, v117
	v_exp_f32_e32 v139, v139
	v_fmamk_f32 v140, v140, 0x3e38aa3b, v116
	v_add_f32_e32 v117, v135, v117
	v_exp_f32_e32 v140, v140
	v_fmamk_f32 v123, v123, 0x3e38aa3b, v116
	v_add_f32_e32 v117, v137, v117
	v_exp_f32_e32 v123, v123
	v_fmamk_f32 v124, v124, 0x3e38aa3b, v116
	v_add_f32_e32 v117, v138, v117
	v_exp_f32_e32 v124, v124
	v_fmamk_f32 v125, v125, 0x3e38aa3b, v116
	v_add_f32_e32 v117, v139, v117
	v_exp_f32_e32 v125, v125
	v_fmamk_f32 v126, v126, 0x3e38aa3b, v116
	v_add_f32_e32 v117, v140, v117
	v_exp_f32_e32 v126, v126
	v_fmamk_f32 v130, v130, 0x3e38aa3b, v116
	v_add_f32_e32 v117, v123, v117
	v_exp_f32_e32 v130, v130
	v_fmamk_f32 v132, v132, 0x3e38aa3b, v116
	v_add_f32_e32 v117, v124, v117
	v_exp_f32_e32 v132, v132
	v_fmamk_f32 v134, v134, 0x3e38aa3b, v116
	v_add_f32_e32 v117, v125, v117
	v_exp_f32_e32 v134, v134
	v_fmac_f32_e32 v116, 0x3e38aa3b, v136
	v_add_f32_e32 v117, v126, v117
	v_exp_f32_e32 v136, v116
	v_add_f32_e32 v116, v130, v117
	v_add_f32_e32 v116, v132, v116
	v_add_f32_e32 v116, v134, v116
	v_add_f32_e32 v141, v136, v116
	v_mov_b64_e32 v[116:117], v[142:143]
	s_branch .LBB0_2004

.LBB0_2007:
	ds_read_b128 v[152:155], v245 offset:13312
	v_cvt_pk_bf16_f32 v156, v127, v131
	v_cvt_pk_bf16_f32 v157, v133, v135
	v_cvt_pk_bf16_f32 v158, v137, v138
	v_cvt_pk_bf16_f32 v159, v139, v140
	v_cvt_pk_bf16_f32 v138, v105, v107
	v_cvt_pk_bf16_f32 v139, v109, v111
	v_cvt_pk_bf16_f32 v140, v113, v114
	v_cvt_pk_bf16_f32 v141, v115, v141
	s_waitcnt lgkmcnt(0)
	v_mfma_f32_16x16x32_bf16 v[48:51], v[152:155], v[156:159], v[48:51]
	v_add_f32_e32 v100, v108, v100
	v_cvt_pk_bf16_f32 v103, v103, v104
	v_cvt_pk_bf16_f32 v104, v106, v108
	v_mfma_f32_16x16x32_bf16 v[64:67], v[152:155], v[138:141], v[64:67]
	ds_read_b128 v[152:155], v245 offset:15616
	ds_read_b128 v[106:109], v245 offset:15680
	v_cvt_pk_bf16_f32 v122, v123, v124
	v_cvt_pk_bf16_f32 v123, v125, v126
	s_waitcnt lgkmcnt(1)
	v_mfma_f32_16x16x32_bf16 v[52:55], v[152:155], v[156:159], v[52:55]
	v_cvt_pk_bf16_f32 v124, v130, v132
	v_cvt_pk_bf16_f32 v125, v134, v136
	v_cvt_pk_bf16_f32 v102, v101, v102
	v_mfma_f32_16x16x32_bf16 v[68:71], v[152:155], v[138:141], v[68:71]
	ds_read_b128 v[152:155], v245 offset:17920
	v_cvt_pk_bf16_f32 v105, v110, v112
	v_add_f32_e32 v100, v110, v100
	s_waitcnt lgkmcnt(0)
	v_mfma_f32_16x16x32_bf16 v[56:59], v[152:155], v[156:159], v[56:59]
	v_add_f32_e32 v100, v112, v100
	s_movk_i32 s34, 0x3fff
	v_add_f32_e32 v119, v119, v100
	v_mfma_f32_16x16x32_bf16 v[72:75], v[152:155], v[138:141], v[72:75]
	ds_read_b128 v[152:155], v245 offset:20224
	v_mfma_f32_16x16x32_bf16 v[52:55], v[106:109], v[122:125], v[52:55]
	v_mfma_f32_16x16x32_bf16 v[68:71], v[106:109], v[102:105], v[68:71]
	ds_read_b128 v[106:109], v245 offset:17984
	s_waitcnt lgkmcnt(1)
	v_mfma_f32_16x16x32_bf16 v[60:63], v[152:155], v[156:159], v[60:63]
	ds_read_b128 v[156:159], v245 offset:13376
	s_waitcnt lgkmcnt(1)
	v_mfma_f32_16x16x32_bf16 v[56:59], v[106:109], v[122:125], v[56:59]
	v_mfma_f32_16x16x32_bf16 v[72:75], v[106:109], v[102:105], v[72:75]
	ds_read_b128 v[106:109], v245 offset:20288
	v_mfma_f32_16x16x32_bf16 v[76:79], v[152:155], v[138:141], v[76:79]
	s_waitcnt lgkmcnt(1)
	v_mfma_f32_16x16x32_bf16 v[48:51], v[156:159], v[122:125], v[48:51]
	v_mfma_f32_16x16x32_bf16 v[64:67], v[156:159], v[102:105], v[64:67]
	s_waitcnt lgkmcnt(0)
	v_mfma_f32_16x16x32_bf16 v[60:63], v[106:109], v[122:125], v[60:63]
	v_mfma_f32_16x16x32_bf16 v[76:79], v[106:109], v[102:105], v[76:79]
	s_andn2_b64 vcc, exec, s[68:69]
	s_cbranch_vccnz .LBB0_1993
	s_branch .LBB0_2009
